# mLSTM scan gate statistics: 64-lane prefix sum and prefix max as DPP row scans instead of ds_bpermute chains (sum reassociated, f32); plus adaLN load batching and attention vmcnt(4)
# speedup vs baseline: 1.0021x; 1.0021x over previous
; #define LAS __attribute__((address_space(3)))
; DI unsigned pk2(float a, float b) { f32x2 v = {a, b}; return __builtin_bit_cast(unsigned, __builtin_convertvector(v, bf16v2)); }
; DI void scan_phase(const Args& A, LAS unsigned char* lds, int wv) {
;     ...
;                 const int s = dir ? 63 - lj : lj;
;                 const float ig = ig_n + big, fg = fg_n + bfg;
;                 if (j + 1 < 36) { const float* gp = G32 + (size_t)(b * TB + SC_POS0(j + 1) + s) * 32 + (dir * 2) * 8 + h; ig_n = gp[0]; fg_n = gp[8]; }
;                 const float lf = fminf(fg, 0.f) - log1pf(__expf(-fabsf(fg)));
;                 float bs = lf;
; #pragma unroll
;                 for (int o = 1; o < 64; o <<= 1) { const float t = __shfl_up(bs, o); if (lj >= o) bs += t; }
;                 const float uu = ig - bs;
;                 float pmx = uu;
; #pragma unroll
;                 for (int o = 1; o < 64; o <<= 1) { const float t = __shfl_up(pmx, o); if (lj >= o) pmx = fmaxf(pmx, t); }
;                 pmx = fmaxf(pmx, m);
;                 const float b_end = __shfl(bs, 63), pm_last = __shfl(pmx, 63);
;                 LAS float* ws_ = wl + s;
;                 ws_[0] = uu * 1.4426950408889634f; ws_[64] = pmx * 1.4426950408889634f; ws_[128] = __expf(m - pmx); ws_[192] = __expf(-(bs + pmx)); ws_[256] = __expf(uu - pm_last);
;                 { const float wv_ = __expf(uu - pm_last), wp_ = __shfl_xor(wv_, 1); if ((s & 1) == 0) wbp[s >> 1] = pk2(wv_, wp_); }
;                 decay = __expf(m - pm_last); m_new = b_end + pm_last;
.LBB0_1227:
	v_add_f32_e32 v66, v161, v66
	s_mov_b32 s6, 0xbfb8aa3b
	v_mul_f32_e64 v67, |v66|, s6
	v_exp_f32_e32 v68, v67
	v_min_f32_e32 v69, 0, v66
	s_mov_b32 s6, 0x3f2aaaab
	v_add_f32_e32 v64, v160, v64
	v_add_f32_e32 v70, 1.0, v68
	v_add_f32_e32 v66, -1.0, v70
	v_sub_f32_e32 v67, v66, v70
	v_sub_f32_e32 v66, v68, v66
	v_add_f32_e32 v67, 1.0, v67
	v_frexp_mant_f32_e32 v71, v70
	v_add_f32_e32 v72, v66, v67
	v_cvt_f64_f32_e32 v[66:67], v70
	v_frexp_exp_i32_f64_e32 v66, v[66:67]
	v_cmp_gt_f32_e32 vcc, s6, v71
	s_mov_b32 s6, 0x3f317218
	s_nop 0
	v_subbrev_co_u32_e32 v66, vcc, 0, v66, vcc
	v_sub_u32_e32 v67, 0, v66
	v_ldexp_f32 v70, v70, v67
	v_add_f32_e32 v71, -1.0, v70
	v_add_f32_e32 v74, 1.0, v70
	v_ldexp_f32 v67, v72, v67
	v_add_f32_e32 v72, 1.0, v71
	v_add_f32_e32 v75, -1.0, v74
	v_sub_f32_e32 v72, v70, v72
	v_sub_f32_e32 v70, v70, v75
	v_add_f32_e32 v72, v67, v72
	v_add_f32_e32 v67, v67, v70
	v_add_f32_e32 v70, v74, v67
	v_rcp_f32_e32 v75, v70
	v_add_f32_e32 v73, v71, v72
	v_sub_f32_e32 v71, v73, v71
	v_sub_f32_e32 v71, v72, v71
	v_sub_f32_e32 v72, v70, v74
	v_sub_f32_e32 v67, v67, v72
	v_mul_f32_e32 v72, v73, v75
	v_mul_f32_e32 v74, v70, v72
	v_fma_f32 v76, v72, v70, -v74
	v_fmac_f32_e32 v76, v72, v67
	v_add_f32_e32 v77, v74, v76
	v_sub_f32_e32 v78, v73, v77
	v_sub_f32_e32 v73, v73, v78
	v_sub_f32_e32 v74, v77, v74
	v_sub_f32_e32 v73, v73, v77
	v_add_f32_e32 v71, v71, v73
	v_sub_f32_e32 v73, v74, v76
	v_add_f32_e32 v71, v73, v71
	v_add_f32_e32 v73, v78, v71
	v_mul_f32_e32 v74, v75, v73
	v_mul_f32_e32 v76, v70, v74
	v_fma_f32 v70, v74, v70, -v76
	v_fmac_f32_e32 v70, v74, v67
	v_sub_f32_e32 v67, v78, v73
	v_add_f32_e32 v67, v71, v67
	v_add_f32_e32 v71, v76, v70
	v_sub_f32_e32 v77, v73, v71
	v_sub_f32_e32 v73, v73, v77
	v_sub_f32_e32 v76, v71, v76
	v_sub_f32_e32 v71, v73, v71
	v_add_f32_e32 v67, v67, v71
	v_sub_f32_e32 v70, v76, v70
	v_cvt_f32_i32_e32 v66, v66
	v_add_f32_e32 v67, v70, v67
	v_add_f32_e32 v70, v72, v74
	v_add_f32_e32 v67, v77, v67
	v_sub_f32_e32 v71, v70, v72
	v_mul_f32_e32 v67, v75, v67
	v_sub_f32_e32 v71, v74, v71
	v_add_f32_e32 v67, v71, v67
	v_mul_f32_e32 v74, 0x3f317218, v66
	v_add_f32_e32 v71, v70, v67
	v_fma_f32 v75, v66, s6, -v74
	v_mul_f32_e32 v72, v71, v71
	v_fmac_f32_e32 v75, 0xb102e308, v66
	v_sub_f32_e32 v66, v71, v70
	v_fmamk_f32 v73, v72, 0x3e9b6dac, v150
	v_sub_f32_e32 v66, v67, v66
	v_add_f32_e32 v67, v74, v75
	v_fmaak_f32 v73, v72, v73, 0x3f2aaada
	v_sub_f32_e32 v70, v67, v74
	v_ldexp_f32 v74, v71, 1
	v_mul_f32_e32 v71, v71, v72
	v_mul_f32_e32 v71, v71, v73
	v_add_f32_e32 v72, v74, v71
	v_sub_f32_e32 v73, v72, v74
	v_ldexp_f32 v66, v66, 1
	v_sub_f32_e32 v71, v71, v73
	v_add_f32_e32 v66, v66, v71
	v_add_f32_e32 v71, v72, v66
	v_sub_f32_e32 v72, v71, v72
	v_sub_f32_e32 v66, v66, v72
	v_add_f32_e32 v72, v67, v71
	v_sub_f32_e32 v73, v72, v67
	v_sub_f32_e32 v74, v72, v73
	v_sub_f32_e32 v70, v75, v70
	v_sub_f32_e32 v67, v67, v74
	v_sub_f32_e32 v71, v71, v73
	v_add_f32_e32 v67, v71, v67
	v_add_f32_e32 v71, v70, v66
	v_sub_f32_e32 v73, v71, v70
	v_sub_f32_e32 v74, v71, v73
	v_sub_f32_e32 v70, v70, v74
	v_sub_f32_e32 v66, v66, v73
	v_add_f32_e32 v67, v71, v67
	v_add_f32_e32 v66, v66, v70
	v_add_f32_e32 v70, v72, v67
	v_sub_f32_e32 v71, v70, v72
	v_sub_f32_e32 v67, v67, v71
	v_add_f32_e32 v66, v66, v67
	s_mov_b32 s6, 0x7f800000
	v_add_f32_e32 v66, v70, v66
	v_cmp_neq_f32_e32 vcc, s6, v68
	s_mov_b32 s6, 0x33800000
	v_and_b32_e32 v67, 64, v151
	v_cndmask_b32_e32 v66, v154, v66, vcc
	v_cmp_ngt_f32_e32 vcc, -1.0, v68
	s_nop 1
	v_cndmask_b32_e32 v66, v155, v66, vcc
	v_cmp_neq_f32_e32 vcc, -1.0, v68
	s_nop 1
	v_cndmask_b32_e32 v66, v156, v66, vcc
	v_cmp_lt_f32_e64 vcc, |v68|, s6
	s_nop 1
	v_cndmask_b32_e32 v66, v66, v68, vcc
	v_sub_f32_e32 v66, v69, v66
	s_nop 1
	v_add_f32_dpp v66, v66, v66 row_shr:1 row_mask:0xf bank_mask:0xf
	s_nop 1
	v_add_f32_dpp v66, v66, v66 row_shr:2 row_mask:0xf bank_mask:0xf
	s_nop 1
	v_add_f32_dpp v66, v66, v66 row_shr:4 row_mask:0xf bank_mask:0xf
	s_nop 1
	v_add_f32_dpp v66, v66, v66 row_shr:8 row_mask:0xf bank_mask:0xf
	s_nop 1
	v_add_f32_dpp v66, v66, v66 row_bcast:15 row_mask:0xa bank_mask:0xf
	s_nop 1
	v_add_f32_dpp v66, v66, v66 row_bcast:31 row_mask:0xc bank_mask:0xf
	v_sub_f32_e32 v64, v64, v66
	ds_bpermute_b32 v165, v152, v66
	v_mov_b32_e32 v68, v64
	s_nop 1
	v_max_f32_dpp v68, v68, v68 row_shr:1 row_mask:0xf bank_mask:0xf
	s_nop 1
	v_max_f32_dpp v68, v68, v68 row_shr:2 row_mask:0xf bank_mask:0xf
	s_nop 1
	v_max_f32_dpp v68, v68, v68 row_shr:4 row_mask:0xf bank_mask:0xf
	s_nop 1
	v_max_f32_dpp v68, v68, v68 row_shr:8 row_mask:0xf bank_mask:0xf
	s_nop 1
	v_max_f32_dpp v68, v68, v68 row_bcast:15 row_mask:0xa bank_mask:0xf
	s_nop 1
	v_max_f32_dpp v68, v68, v68 row_bcast:31 row_mask:0xc bank_mask:0xf
	s_waitcnt lgkmcnt(0)
	v_max_f32_e32 v68, v68, v68
	v_max_f32_e32 v69, v171, v171
	v_max_f32_e32 v68, v68, v69
	ds_bpermute_b32 v166, v152, v68
	v_mul_f32_e32 v70, 0x3fb8aa3b, v64
	v_add_f32_e32 v66, v66, v68
	v_lshl_add_u32 v69, v65, 2, s47
	v_mul_f32_e32 v71, 0x3fb8aa3b, v68
	s_waitcnt lgkmcnt(0)
	v_sub_f32_e32 v64, v64, v166
	v_mul_f32_e32 v66, 0xbfb8aa3b, v66
	v_mul_f32_e32 v64, 0x3fb8aa3b, v64
	ds_write2st64_b32 v69, v70, v71 offset1:1
	v_sub_f32_e32 v70, v171, v68
	v_exp_f32_e32 v68, v66
	v_exp_f32_e32 v66, v64
	v_xor_b32_e32 v71, 1, v151
	v_add_u32_e32 v64, 64, v67
	v_cmp_lt_i32_e32 vcc, v71, v64
	v_mul_f32_e32 v70, 0x3fb8aa3b, v70
	v_exp_f32_e32 v70, v70
	v_cndmask_b32_e32 v67, v151, v71, vcc
	v_lshlrev_b32_e32 v167, 2, v67
	ds_bpermute_b32 v67, v167, v66
	ds_write2st64_b32 v69, v70, v68 offset0:2 offset1:3
	ds_write_b32 v69, v66 offset:1024
	v_and_b32_e32 v68, 1, v65
	v_cmp_eq_u32_e32 vcc, 0, v68
	s_and_saveexec_b64 s[6:7], vcc
	s_cbranch_execz .LBB0_1229
	v_lshl_add_u32 v65, v65, 1, s47
	s_waitcnt lgkmcnt(0)
	v_cvt_pk_bf16_f32 v66, v66, v67
	ds_write_b32 v65, v66 offset:2304
